# v52 with MLA priorities changed: odd (younger) waves stay at prio 1 throughout, even waves prio 0 in QK scores / 1 in softmax+PV
# speedup vs baseline: 1.0031x; 1.0031x over previous
.LBB0_1783:
	s_waitcnt vmcnt(0) lgkmcnt(0)
	s_barrier
	s_setprio 0
